# scan loader late-round wait without the per-round L1/L2 invalidate (tile lines are never cached on the consumer XCD before publication; grid barriers invalidate)
# speedup vs baseline: 1.0094x; 1.0094x over previous
.LBB0_1123:
	s_waitcnt lgkmcnt(0)
	s_mov_b32 s51, s46
